# MLA reference-update path: rescale factor clamped to exp2(-max(d,0)) so a very negative first-tile max cannot overflow (robustness; no change in the common path)
# baseline (speedup 1.0000x reference)
; DI float xhalf_max(float x) { auto r = __builtin_amdgcn_permlane32_swap(__float_as_uint(x), __float_as_uint(x), false, false); return fmaxf(__uint_as_float(r[0]), __uint_as_float(r[1])); }
; DI float fexp2(float x) { return __builtin_amdgcn_exp2f(x); }
;     ...
;                 mx = xhalf_max(mx);
;                 const float mn = fmaxf(m, mx), alpha = fexp2(m - mn);
;                 m = mn;
;                 f32x4 ps4 = {0.f, 0.f, 0.f, 0.f};
;                 const float nmn = -mn;
;                 const f32x4 nm4 = {nmn, nmn, nmn, nmn};
;                 if (__builtin_amdgcn_ballot_w64(alpha != 1.f) != 0) { o0 *= alpha; o1 *= alpha; }
.Lm3_rare_e:
	s_nop 1
	v_cndmask_b32_e64 v122, 0, v120, vcc
	s_mov_b64 s[20:21], 0
	v_sub_f32_e32 v156, v156, v122
	v_sub_f32_e32 v157, v157, v122
	v_sub_f32_e32 v158, v158, v122
	v_sub_f32_e32 v159, v159, v122
	v_sub_f32_e32 v160, v160, v122
	v_sub_f32_e32 v161, v161, v122
	v_sub_f32_e32 v162, v162, v122
	v_sub_f32_e32 v163, v163, v122
	v_sub_f32_e32 v164, v164, v122
	v_sub_f32_e32 v165, v165, v122
	v_sub_f32_e32 v166, v166, v122
	v_sub_f32_e32 v167, v167, v122
	v_sub_f32_e32 v168, v168, v122
	v_sub_f32_e32 v169, v169, v122
	v_sub_f32_e32 v170, v170, v122
	v_sub_f32_e32 v171, v171, v122
	v_sub_f32_e32 v50, v50, v122
	v_sub_f32_e32 v51, v51, v122
	v_sub_f32_e32 v52, v52, v122
	v_sub_f32_e32 v53, v53, v122
	v_sub_f32_e32 v54, v54, v122
	v_sub_f32_e32 v55, v55, v122
	v_sub_f32_e32 v56, v56, v122
	v_sub_f32_e32 v57, v57, v122
	v_sub_f32_e32 v58, v58, v122
	v_sub_f32_e32 v59, v59, v122
	v_sub_f32_e32 v60, v60, v122
	v_sub_f32_e32 v61, v61, v122
	v_sub_f32_e32 v62, v62, v122
	v_sub_f32_e32 v63, v63, v122
	v_sub_f32_e32 v64, v64, v122
	v_sub_f32_e32 v65, v65, v122
	v_sub_f32_e32 v34, v34, v122
	v_sub_f32_e32 v35, v35, v122
	v_sub_f32_e32 v36, v36, v122
	v_sub_f32_e32 v37, v37, v122
	v_sub_f32_e32 v38, v38, v122
	v_sub_f32_e32 v39, v39, v122
	v_sub_f32_e32 v40, v40, v122
	v_sub_f32_e32 v41, v41, v122
	v_sub_f32_e32 v42, v42, v122
	v_sub_f32_e32 v43, v43, v122
	v_sub_f32_e32 v44, v44, v122
	v_sub_f32_e32 v45, v45, v122
	v_sub_f32_e32 v46, v46, v122
	v_sub_f32_e32 v47, v47, v122
	v_sub_f32_e32 v48, v48, v122
	v_sub_f32_e32 v49, v49, v122
	v_max_f32_e32 v122, 0, v122
	v_exp_f32_e64 v122, -v122
	s_nop 0
	v_mul_f32_e32 v2, v2, v122
	v_mul_f32_e32 v3, v3, v122
	v_mul_f32_e32 v4, v4, v122
	v_mul_f32_e32 v5, v5, v122
	v_mul_f32_e32 v6, v6, v122
	v_mul_f32_e32 v7, v7, v122
	v_mul_f32_e32 v8, v8, v122
	v_mul_f32_e32 v9, v9, v122
	v_mul_f32_e32 v10, v10, v122
	v_mul_f32_e32 v11, v11, v122
	v_mul_f32_e32 v12, v12, v122
	v_mul_f32_e32 v13, v13, v122
	v_mul_f32_e32 v14, v14, v122
	v_mul_f32_e32 v15, v15, v122
	v_mul_f32_e32 v16, v16, v122
	v_mul_f32_e32 v17, v17, v122
	v_mul_f32_e32 v18, v18, v122
	v_mul_f32_e32 v19, v19, v122
	v_mul_f32_e32 v20, v20, v122
	v_mul_f32_e32 v21, v21, v122
	v_mul_f32_e32 v22, v22, v122
	v_mul_f32_e32 v23, v23, v122
	v_mul_f32_e32 v24, v24, v122
	v_mul_f32_e32 v25, v25, v122
	v_mul_f32_e32 v26, v26, v122
	v_mul_f32_e32 v27, v27, v122
	v_mul_f32_e32 v28, v28, v122
	v_mul_f32_e32 v29, v29, v122
	v_mul_f32_e32 v30, v30, v122
	v_mul_f32_e32 v31, v31, v122
	v_mul_f32_e32 v32, v32, v122
	v_mul_f32_e32 v33, v33, v122
	v_mul_f32_e32 v135, v135, v122
	s_branch .Lm3_back_e
.Lm3_rare_o:
	s_nop 1
	v_cndmask_b32_e64 v122, 0, v120, vcc
	s_mov_b64 s[20:21], 0
	v_sub_f32_e32 v156, v156, v122
	v_sub_f32_e32 v157, v157, v122
	v_sub_f32_e32 v158, v158, v122
	v_sub_f32_e32 v159, v159, v122
	v_sub_f32_e32 v160, v160, v122
	v_sub_f32_e32 v161, v161, v122
	v_sub_f32_e32 v162, v162, v122
	v_sub_f32_e32 v163, v163, v122
	v_sub_f32_e32 v164, v164, v122
	v_sub_f32_e32 v165, v165, v122
	v_sub_f32_e32 v166, v166, v122
	v_sub_f32_e32 v167, v167, v122
	v_sub_f32_e32 v168, v168, v122
	v_sub_f32_e32 v169, v169, v122
	v_sub_f32_e32 v170, v170, v122
	v_sub_f32_e32 v171, v171, v122
	v_sub_f32_e32 v176, v176, v122
	v_sub_f32_e32 v177, v177, v122
	v_sub_f32_e32 v178, v178, v122
	v_sub_f32_e32 v179, v179, v122
	v_sub_f32_e32 v180, v180, v122
	v_sub_f32_e32 v181, v181, v122
	v_sub_f32_e32 v182, v182, v122
	v_sub_f32_e32 v183, v183, v122
	v_sub_f32_e32 v184, v184, v122
	v_sub_f32_e32 v185, v185, v122
	v_sub_f32_e32 v186, v186, v122
	v_sub_f32_e32 v187, v187, v122
	v_sub_f32_e32 v188, v188, v122
	v_sub_f32_e32 v189, v189, v122
	v_sub_f32_e32 v190, v190, v122
	v_sub_f32_e32 v191, v191, v122
	v_sub_f32_e32 v192, v192, v122
	v_sub_f32_e32 v193, v193, v122
	v_sub_f32_e32 v194, v194, v122
	v_sub_f32_e32 v195, v195, v122
	v_sub_f32_e32 v196, v196, v122
	v_sub_f32_e32 v197, v197, v122
	v_sub_f32_e32 v198, v198, v122
	v_sub_f32_e32 v199, v199, v122
	v_sub_f32_e32 v200, v200, v122
	v_sub_f32_e32 v201, v201, v122
	v_sub_f32_e32 v202, v202, v122
	v_sub_f32_e32 v203, v203, v122
	v_sub_f32_e32 v204, v204, v122
	v_sub_f32_e32 v205, v205, v122
	v_sub_f32_e32 v206, v206, v122
	v_sub_f32_e32 v207, v207, v122
	v_max_f32_e32 v122, 0, v122
	v_exp_f32_e64 v122, -v122
	s_nop 0
	v_mul_f32_e32 v2, v2, v122
	v_mul_f32_e32 v3, v3, v122
	v_mul_f32_e32 v4, v4, v122
	v_mul_f32_e32 v5, v5, v122
	v_mul_f32_e32 v6, v6, v122
	v_mul_f32_e32 v7, v7, v122
	v_mul_f32_e32 v8, v8, v122
	v_mul_f32_e32 v9, v9, v122
	v_mul_f32_e32 v10, v10, v122
	v_mul_f32_e32 v11, v11, v122
	v_mul_f32_e32 v12, v12, v122
	v_mul_f32_e32 v13, v13, v122
	v_mul_f32_e32 v14, v14, v122
	v_mul_f32_e32 v15, v15, v122
	v_mul_f32_e32 v16, v16, v122
	v_mul_f32_e32 v17, v17, v122
	v_mul_f32_e32 v18, v18, v122
	v_mul_f32_e32 v19, v19, v122
	v_mul_f32_e32 v20, v20, v122
	v_mul_f32_e32 v21, v21, v122
	v_mul_f32_e32 v22, v22, v122
	v_mul_f32_e32 v23, v23, v122
	v_mul_f32_e32 v24, v24, v122
	v_mul_f32_e32 v25, v25, v122
	v_mul_f32_e32 v26, v26, v122
	v_mul_f32_e32 v27, v27, v122
	v_mul_f32_e32 v28, v28, v122
	v_mul_f32_e32 v29, v29, v122
	v_mul_f32_e32 v30, v30, v122
	v_mul_f32_e32 v31, v31, v122
	v_mul_f32_e32 v32, v32, v122
	v_mul_f32_e32 v33, v33, v122
	v_mul_f32_e32 v135, v135, v122
	s_branch .Lm3_back_o
